# tanh-gelu arithmetic of the S5 output epilogue folded (exp2 argument by one fma, y - y*rcp(1+e) tail)
# speedup vs baseline: 1.0198x; 1.0058x over previous
.LBB0_920:
	v_mov_b32_e32 v247, 0x3dd2d3e7
	v_mul_f32_e32 v151, v124, v124
	v_fmaak_f32 v151, v247, v151, 0x40135761
	v_mul_f32_e32 v151, v151, v124
	v_exp_f32_e32 v151, v151
	s_mul_i32 s9, s24, 0xffffd00
	s_lshl_b32 s25, s25, 12
	v_add_u32_e32 v152, s9, v144
	v_add_f32_e32 v153, 1.0, v151
	v_lshl_add_u32 v151, v152, 4, s25
	s_lshl_b32 s18, s24, 4
	v_mul_f32_e32 v154, v125, v125
	v_fmaak_f32 v154, v247, v154, 0x40135761
	v_mul_f32_e32 v154, v154, v125
	v_exp_f32_e32 v154, v154
	v_rcp_f32_e32 v152, v153
	v_add_f32_e32 v153, 1.0, v154
	v_fma_f32 v124, -v124, v152, v124
	v_mul_f32_e32 v154, v126, v126
	v_fmaak_f32 v154, v247, v154, 0x40135761
	v_mul_f32_e32 v154, v154, v126
	v_exp_f32_e32 v154, v154
	v_rcp_f32_e32 v152, v153
	v_add_f32_e32 v153, 1.0, v154
	v_fma_f32 v125, -v125, v152, v125
	v_cvt_pk_bf16_f32 v124, v124, v125
	v_mul_f32_e32 v154, v127, v127
	v_fmaak_f32 v154, v247, v154, 0x40135761
	v_mul_f32_e32 v154, v154, v127
	v_exp_f32_e32 v154, v154
	v_rcp_f32_e32 v125, v153
	v_add_f32_e32 v152, 1.0, v154
	v_fma_f32 v125, -v126, v125, v126
	v_mul_f32_e32 v153, v120, v120
	v_fmaak_f32 v153, v247, v153, 0x40135761
	v_mul_f32_e32 v153, v153, v120
	v_exp_f32_e32 v153, v153
	v_rcp_f32_e32 v126, v152
	v_add_f32_e32 v152, 1.0, v153
	v_fma_f32 v126, -v127, v126, v127
	v_cvt_pk_bf16_f32 v125, v125, v126
	v_mul_f32_e32 v153, v121, v121
	v_fmaak_f32 v153, v247, v153, 0x40135761
	v_mul_f32_e32 v153, v153, v121
	v_exp_f32_e32 v153, v153
	v_rcp_f32_e32 v126, v152
	v_add_f32_e32 v127, 1.0, v153
	v_fma_f32 v120, -v120, v126, v120
	v_mul_f32_e32 v152, v122, v122
	v_fmaak_f32 v152, v247, v152, 0x40135761
	v_mul_f32_e32 v152, v152, v122
	v_exp_f32_e32 v152, v152
	v_rcp_f32_e32 v126, v127
	v_add_f32_e32 v127, 1.0, v152
	v_fma_f32 v121, -v121, v126, v121
	v_cvt_pk_bf16_f32 v126, v120, v121
	v_mul_f32_e32 v152, 0x3d372713, v123
	v_mul_f32_e32 v152, v123, v152
	v_fma_f32 v152, v123, v152, v123
	v_mul_f32_e32 v152, 0x3f4c422a, v152
	v_add_f32_e32 v152, v152, v152
	v_mul_f32_e32 v152, 0x3fb8aa3b, v152
	v_exp_f32_e32 v152, v152
	v_rcp_f32_e32 v120, v127
	v_add_f32_e32 v121, 1.0, v152
	v_fma_f32 v120, -v122, v120, v122
	v_rcp_f32_e32 v121, v121
	s_nop 0
	v_add_f32_e32 v121, v121, v121
	v_sub_f32_e32 v121, 1.0, v121
	v_mul_f32_e32 v122, 0.5, v123
	v_add_f32_e32 v121, 1.0, v121
	v_mul_f32_e32 v121, v122, v121
	v_mul_f32_e32 v122, v116, v116
	v_fmaak_f32 v122, v247, v122, 0x40135761
	v_mul_f32_e32 v122, v122, v116
	v_exp_f32_e32 v122, v122
	v_cvt_pk_bf16_f32 v127, v120, v121
	v_add_u32_e32 v120, v151, v146
	v_ashrrev_i32_e32 v121, 31, v120
	v_add_f32_e32 v122, 1.0, v122
	s_ashr_i32 s19, s18, 31
	v_lshlrev_b64 v[120:121], 10, v[120:121]
	v_lshl_add_u64 v[120:121], s[60:61], 0, v[120:121]
	s_lshl_b64 s[18:19], s[18:19], 1
	v_lshl_add_u64 v[120:121], v[120:121], 0, s[18:19]
	v_lshl_add_u64 v[120:121], v[120:121], 0, v[136:137]
	global_store_dwordx4 v[120:121], v[124:127], off
	v_mul_f32_e32 v123, v117, v117
	v_fmaak_f32 v123, v247, v123, 0x40135761
	v_mul_f32_e32 v123, v123, v117
	v_exp_f32_e32 v123, v123
	v_rcp_f32_e32 v120, v122
	v_add_f32_e32 v121, 1.0, v123
	v_fma_f32 v116, -v116, v120, v116
	v_mul_f32_e32 v122, v118, v118
	v_fmaak_f32 v122, v247, v122, 0x40135761
	v_mul_f32_e32 v122, v122, v118
	v_exp_f32_e32 v122, v122
	v_rcp_f32_e32 v120, v121
	v_add_f32_e32 v121, 1.0, v122
	v_fma_f32 v117, -v117, v120, v117
	v_cvt_pk_bf16_f32 v116, v116, v117
	v_mul_f32_e32 v122, v119, v119
	v_fmaak_f32 v122, v247, v122, 0x40135761
	v_mul_f32_e32 v122, v122, v119
	v_exp_f32_e32 v122, v122
	v_rcp_f32_e32 v117, v121
	v_add_f32_e32 v120, 1.0, v122
	v_fma_f32 v117, -v118, v117, v118
	v_mul_f32_e32 v121, v112, v112
	v_fmaak_f32 v121, v247, v121, 0x40135761
	v_mul_f32_e32 v121, v121, v112
	v_exp_f32_e32 v121, v121
	v_rcp_f32_e32 v118, v120
	v_add_f32_e32 v120, 1.0, v121
	v_fma_f32 v118, -v119, v118, v119
	v_cvt_pk_bf16_f32 v117, v117, v118
	v_mul_f32_e32 v121, v113, v113
	v_fmaak_f32 v121, v247, v121, 0x40135761
	v_mul_f32_e32 v121, v121, v113
	v_exp_f32_e32 v121, v121
	v_rcp_f32_e32 v118, v120
	v_add_f32_e32 v119, 1.0, v121
	v_fma_f32 v112, -v112, v118, v112
	v_mul_f32_e32 v120, v114, v114
	v_fmaak_f32 v120, v247, v120, 0x40135761
	v_mul_f32_e32 v120, v120, v114
	v_exp_f32_e32 v120, v120
	v_rcp_f32_e32 v118, v119
	v_add_f32_e32 v119, 1.0, v120
	v_fma_f32 v113, -v113, v118, v113
	v_cvt_pk_bf16_f32 v118, v112, v113
	v_mul_f32_e32 v120, 0x3d372713, v115
	v_mul_f32_e32 v120, v115, v120
	v_fma_f32 v120, v115, v120, v115
	v_mul_f32_e32 v120, 0x3f4c422a, v120
	v_add_f32_e32 v120, v120, v120
	v_mul_f32_e32 v120, 0x3fb8aa3b, v120
	v_exp_f32_e32 v120, v120
	v_rcp_f32_e32 v112, v119
	v_add_f32_e32 v113, 1.0, v120
	v_fma_f32 v112, -v114, v112, v114
	v_rcp_f32_e32 v113, v113
	s_nop 0
	v_add_f32_e32 v113, v113, v113
	v_sub_f32_e32 v113, 1.0, v113
	v_mul_f32_e32 v114, 0.5, v115
	v_add_f32_e32 v113, 1.0, v113
	v_mul_f32_e32 v113, v114, v113
	v_mul_f32_e32 v114, v108, v108
	v_fmaak_f32 v114, v247, v114, 0x40135761
	v_mul_f32_e32 v114, v114, v108
	v_exp_f32_e32 v114, v114
	v_cvt_pk_bf16_f32 v119, v112, v113
	v_add_u32_e32 v112, v151, v147
	v_ashrrev_i32_e32 v113, 31, v112
	v_add_f32_e32 v114, 1.0, v114
	v_lshlrev_b64 v[112:113], 10, v[112:113]
	v_lshl_add_u64 v[112:113], s[60:61], 0, v[112:113]
	v_lshl_add_u64 v[112:113], v[112:113], 0, s[18:19]
	v_lshl_add_u64 v[112:113], v[112:113], 0, v[136:137]
	global_store_dwordx4 v[112:113], v[116:119], off
	v_mul_f32_e32 v115, v109, v109
	v_fmaak_f32 v115, v247, v115, 0x40135761
	v_mul_f32_e32 v115, v115, v109
	v_exp_f32_e32 v115, v115
	v_rcp_f32_e32 v113, v114
	v_add_f32_e32 v114, 1.0, v115
	v_fma_f32 v108, -v108, v113, v108
	v_mul_f32_e32 v115, v110, v110
	v_fmaak_f32 v115, v247, v115, 0x40135761
	v_mul_f32_e32 v115, v115, v110
	v_exp_f32_e32 v115, v115
	v_rcp_f32_e32 v113, v114
	v_add_f32_e32 v114, 1.0, v115
	v_fma_f32 v109, -v109, v113, v109
	v_cvt_pk_bf16_f32 v108, v108, v109
	v_mul_f32_e32 v115, v111, v111
	v_fmaak_f32 v115, v247, v115, 0x40135761
	v_mul_f32_e32 v115, v115, v111
	v_exp_f32_e32 v115, v115
	v_rcp_f32_e32 v109, v114
	v_add_f32_e32 v113, 1.0, v115
	v_fma_f32 v109, -v110, v109, v110
	v_mul_f32_e32 v114, v104, v104
	v_fmaak_f32 v114, v247, v114, 0x40135761
	v_mul_f32_e32 v114, v114, v104
	v_exp_f32_e32 v114, v114
	v_rcp_f32_e32 v110, v113
	v_add_f32_e32 v113, 1.0, v114
	v_fma_f32 v110, -v111, v110, v111
	v_cvt_pk_bf16_f32 v109, v109, v110
	v_mul_f32_e32 v114, v105, v105
	v_fmaak_f32 v114, v247, v114, 0x40135761
	v_mul_f32_e32 v114, v114, v105
	v_exp_f32_e32 v114, v114
	v_rcp_f32_e32 v110, v113
	v_add_f32_e32 v111, 1.0, v114
	v_fma_f32 v104, -v104, v110, v104
	v_mul_f32_e32 v113, v106, v106
	v_fmaak_f32 v113, v247, v113, 0x40135761
	v_mul_f32_e32 v113, v113, v106
	v_exp_f32_e32 v113, v113
	v_rcp_f32_e32 v110, v111
	v_add_f32_e32 v111, 1.0, v113
	v_fma_f32 v105, -v105, v110, v105
	v_cvt_pk_bf16_f32 v110, v104, v105
	v_mul_f32_e32 v113, 0x3d372713, v107
	v_mul_f32_e32 v113, v107, v113
	v_fma_f32 v113, v107, v113, v107
	v_mul_f32_e32 v113, 0x3f4c422a, v113
	v_add_f32_e32 v113, v113, v113
	v_mul_f32_e32 v113, 0x3fb8aa3b, v113
	v_exp_f32_e32 v113, v113
	v_rcp_f32_e32 v104, v111
	v_add_f32_e32 v105, 1.0, v113
	v_fma_f32 v104, -v106, v104, v106
	v_rcp_f32_e32 v105, v105
	s_nop 0
	v_add_f32_e32 v105, v105, v105
	v_sub_f32_e32 v105, 1.0, v105
	v_mul_f32_e32 v106, 0.5, v107
	v_add_f32_e32 v105, 1.0, v105
	v_mul_f32_e32 v105, v106, v105
	v_cvt_pk_bf16_f32 v111, v104, v105
	v_mul_f32_e32 v105, 0x3d372713, v100
	v_mul_f32_e32 v105, v100, v105
	v_fma_f32 v105, v100, v105, v100
	v_mul_f32_e32 v105, 0x3f4c422a, v105
	v_add_f32_e32 v105, v105, v105
	v_mul_f32_e32 v105, 0x3fb8aa3b, v105
	v_exp_f32_e32 v106, v105
	v_or_b32_e32 v112, 0x100, v151
	v_add_u32_e32 v104, v112, v146
	v_ashrrev_i32_e32 v105, 31, v104
	v_add_f32_e32 v106, 1.0, v106
	v_lshlrev_b64 v[104:105], 10, v[104:105]
	v_lshl_add_u64 v[104:105], s[60:61], 0, v[104:105]
	v_lshl_add_u64 v[104:105], v[104:105], 0, s[18:19]
	v_lshl_add_u64 v[104:105], v[104:105], 0, v[136:137]
	global_store_dwordx4 v[104:105], v[108:111], off
	v_mul_f32_e32 v107, v101, v101
	v_fmaak_f32 v107, v247, v107, 0x40135761
	v_mul_f32_e32 v107, v107, v101
	v_exp_f32_e32 v107, v107
	v_rcp_f32_e32 v104, v106
	s_nop 0
	v_add_f32_e32 v104, v104, v104
	v_sub_f32_e32 v104, 1.0, v104
	v_add_f32_e32 v105, 1.0, v107
	v_mul_f32_e32 v100, 0.5, v100
	v_add_f32_e32 v104, 1.0, v104
	v_mul_f32_e32 v100, v100, v104
	v_mul_f32_e32 v106, v102, v102
	v_fmaak_f32 v106, v247, v106, 0x40135761
	v_mul_f32_e32 v106, v106, v102
	v_exp_f32_e32 v106, v106
	v_rcp_f32_e32 v104, v105
	v_add_f32_e32 v105, 1.0, v106
	v_fma_f32 v101, -v101, v104, v101
	v_cvt_pk_bf16_f32 v100, v100, v101
	v_mul_f32_e32 v106, v103, v103
	v_fmaak_f32 v106, v247, v106, 0x40135761
	v_mul_f32_e32 v106, v106, v103
	v_exp_f32_e32 v106, v106
	v_rcp_f32_e32 v101, v105
	v_add_f32_e32 v104, 1.0, v106
	v_fma_f32 v101, -v102, v101, v102
	v_mul_f32_e32 v105, v96, v96
	v_fmaak_f32 v105, v247, v105, 0x40135761
	v_mul_f32_e32 v105, v105, v96
	v_exp_f32_e32 v105, v105
	v_rcp_f32_e32 v102, v104
	v_add_f32_e32 v104, 1.0, v105
	v_fma_f32 v102, -v103, v102, v103
	v_cvt_pk_bf16_f32 v101, v101, v102
	v_mul_f32_e32 v105, v97, v97
	v_fmaak_f32 v105, v247, v105, 0x40135761
	v_mul_f32_e32 v105, v105, v97
	v_exp_f32_e32 v105, v105
	v_rcp_f32_e32 v102, v104
	v_add_f32_e32 v103, 1.0, v105
	v_fma_f32 v96, -v96, v102, v96
	v_mul_f32_e32 v104, v98, v98
	v_fmaak_f32 v104, v247, v104, 0x40135761
	v_mul_f32_e32 v104, v104, v98
	v_exp_f32_e32 v104, v104
	v_rcp_f32_e32 v102, v103
	v_add_f32_e32 v103, 1.0, v104
	v_fma_f32 v97, -v97, v102, v97
	v_cvt_pk_bf16_f32 v102, v96, v97
	v_mul_f32_e32 v104, 0x3d372713, v99
	v_mul_f32_e32 v104, v99, v104
	v_fma_f32 v104, v99, v104, v99
	v_mul_f32_e32 v104, 0x3f4c422a, v104
	v_add_f32_e32 v104, v104, v104
	v_mul_f32_e32 v104, 0x3fb8aa3b, v104
	v_exp_f32_e32 v104, v104
	v_rcp_f32_e32 v96, v103
	v_add_f32_e32 v97, 1.0, v104
	v_fma_f32 v96, -v98, v96, v98
	v_rcp_f32_e32 v97, v97
	s_nop 0
	v_add_f32_e32 v97, v97, v97
	v_sub_f32_e32 v97, 1.0, v97
	v_mul_f32_e32 v98, 0.5, v99
	v_add_f32_e32 v97, 1.0, v97
	v_mul_f32_e32 v97, v98, v97
	v_mul_f32_e32 v98, v92, v92
	v_fmaak_f32 v98, v247, v98, 0x40135761
	v_mul_f32_e32 v98, v98, v92
	v_exp_f32_e32 v98, v98
	v_cvt_pk_bf16_f32 v103, v96, v97
	v_add_u32_e32 v96, v112, v147
	v_ashrrev_i32_e32 v97, 31, v96
	v_add_f32_e32 v98, 1.0, v98
	v_lshlrev_b64 v[96:97], 10, v[96:97]
	v_lshl_add_u64 v[96:97], s[60:61], 0, v[96:97]
	v_lshl_add_u64 v[96:97], v[96:97], 0, s[18:19]
	v_lshl_add_u64 v[96:97], v[96:97], 0, v[136:137]
	global_store_dwordx4 v[96:97], v[100:103], off
	v_mul_f32_e32 v99, v93, v93
	v_fmaak_f32 v99, v247, v99, 0x40135761
	v_mul_f32_e32 v99, v99, v93
	v_exp_f32_e32 v99, v99
	v_rcp_f32_e32 v97, v98
	v_add_f32_e32 v98, 1.0, v99
	v_fma_f32 v92, -v92, v97, v92
	v_mul_f32_e32 v99, v94, v94
	v_fmaak_f32 v99, v247, v99, 0x40135761
	v_mul_f32_e32 v99, v99, v94
	v_exp_f32_e32 v99, v99
	v_rcp_f32_e32 v97, v98
	v_add_f32_e32 v98, 1.0, v99
	v_fma_f32 v93, -v93, v97, v93
	v_cvt_pk_bf16_f32 v92, v92, v93
	v_mul_f32_e32 v99, v95, v95
	v_fmaak_f32 v99, v247, v99, 0x40135761
	v_mul_f32_e32 v99, v99, v95
	v_exp_f32_e32 v99, v99
	v_rcp_f32_e32 v93, v98
	v_add_f32_e32 v97, 1.0, v99
	v_fma_f32 v93, -v94, v93, v94
	v_mul_f32_e32 v98, v88, v88
	v_fmaak_f32 v98, v247, v98, 0x40135761
	v_mul_f32_e32 v98, v98, v88
	v_exp_f32_e32 v98, v98
	v_rcp_f32_e32 v94, v97
	v_add_f32_e32 v97, 1.0, v98
	v_fma_f32 v94, -v95, v94, v95
	v_cvt_pk_bf16_f32 v93, v93, v94
	v_mul_f32_e32 v98, v89, v89
	v_fmaak_f32 v98, v247, v98, 0x40135761
	v_mul_f32_e32 v98, v98, v89
	v_exp_f32_e32 v98, v98
	v_rcp_f32_e32 v94, v97
	v_add_f32_e32 v95, 1.0, v98
	v_fma_f32 v88, -v88, v94, v88
	v_mul_f32_e32 v97, v90, v90
	v_fmaak_f32 v97, v247, v97, 0x40135761
	v_mul_f32_e32 v97, v97, v90
	v_exp_f32_e32 v97, v97
	v_rcp_f32_e32 v94, v95
	v_add_f32_e32 v95, 1.0, v97
	v_fma_f32 v89, -v89, v94, v89
	v_cvt_pk_bf16_f32 v94, v88, v89
	v_mul_f32_e32 v97, 0x3d372713, v91
	v_mul_f32_e32 v97, v91, v97
	v_fma_f32 v97, v91, v97, v91
	v_mul_f32_e32 v97, 0x3f4c422a, v97
	v_add_f32_e32 v97, v97, v97
	v_mul_f32_e32 v97, 0x3fb8aa3b, v97
	v_exp_f32_e32 v97, v97
	v_rcp_f32_e32 v88, v95
	v_add_f32_e32 v89, 1.0, v97
	v_fma_f32 v88, -v90, v88, v90
	v_rcp_f32_e32 v89, v89
	s_nop 0
	v_add_f32_e32 v89, v89, v89
	v_sub_f32_e32 v89, 1.0, v89
	v_mul_f32_e32 v90, 0.5, v91
	v_add_f32_e32 v89, 1.0, v89
	v_mul_f32_e32 v89, v90, v89
	v_cvt_pk_bf16_f32 v95, v88, v89
	v_mul_f32_e32 v89, 0x3d372713, v84
	v_mul_f32_e32 v89, v84, v89
	v_fma_f32 v89, v84, v89, v84
	v_mul_f32_e32 v89, 0x3f4c422a, v89
	v_add_f32_e32 v89, v89, v89
	v_mul_f32_e32 v89, 0x3fb8aa3b, v89
	v_exp_f32_e32 v90, v89
	v_or_b32_e32 v96, 0x200, v151
	v_add_u32_e32 v88, v96, v146
	v_ashrrev_i32_e32 v89, 31, v88
	v_add_f32_e32 v90, 1.0, v90
	v_lshlrev_b64 v[88:89], 10, v[88:89]
	v_lshl_add_u64 v[88:89], s[60:61], 0, v[88:89]
	v_lshl_add_u64 v[88:89], v[88:89], 0, s[18:19]
	v_lshl_add_u64 v[88:89], v[88:89], 0, v[136:137]
	global_store_dwordx4 v[88:89], v[92:95], off
	v_mul_f32_e32 v91, v85, v85
	v_fmaak_f32 v91, v247, v91, 0x40135761
	v_mul_f32_e32 v91, v91, v85
	v_exp_f32_e32 v91, v91
	v_rcp_f32_e32 v88, v90
	s_nop 0
	v_add_f32_e32 v88, v88, v88
	v_sub_f32_e32 v88, 1.0, v88
	v_add_f32_e32 v89, 1.0, v91
	v_mul_f32_e32 v84, 0.5, v84
	v_add_f32_e32 v88, 1.0, v88
	v_mul_f32_e32 v84, v84, v88
	v_mul_f32_e32 v90, v86, v86
	v_fmaak_f32 v90, v247, v90, 0x40135761
	v_mul_f32_e32 v90, v90, v86
	v_exp_f32_e32 v90, v90
	v_rcp_f32_e32 v88, v89
	v_add_f32_e32 v89, 1.0, v90
	v_fma_f32 v85, -v85, v88, v85
	v_cvt_pk_bf16_f32 v84, v84, v85
	v_mul_f32_e32 v90, v87, v87
	v_fmaak_f32 v90, v247, v90, 0x40135761
	v_mul_f32_e32 v90, v90, v87
	v_exp_f32_e32 v90, v90
	v_rcp_f32_e32 v85, v89
	v_add_f32_e32 v88, 1.0, v90
	v_fma_f32 v85, -v86, v85, v86
	v_mul_f32_e32 v89, v80, v80
	v_fmaak_f32 v89, v247, v89, 0x40135761
	v_mul_f32_e32 v89, v89, v80
	v_exp_f32_e32 v89, v89
	v_rcp_f32_e32 v86, v88
	v_add_f32_e32 v88, 1.0, v89
	v_fma_f32 v86, -v87, v86, v87
	v_cvt_pk_bf16_f32 v85, v85, v86
	v_mul_f32_e32 v89, v81, v81
	v_fmaak_f32 v89, v247, v89, 0x40135761
	v_mul_f32_e32 v89, v89, v81
	v_exp_f32_e32 v89, v89
	v_rcp_f32_e32 v86, v88
	v_add_f32_e32 v87, 1.0, v89
	v_fma_f32 v80, -v80, v86, v80
	v_mul_f32_e32 v88, v82, v82
	v_fmaak_f32 v88, v247, v88, 0x40135761
	v_mul_f32_e32 v88, v88, v82
	v_exp_f32_e32 v88, v88
	v_rcp_f32_e32 v86, v87
	v_add_f32_e32 v87, 1.0, v88
	v_fma_f32 v81, -v81, v86, v81
	v_cvt_pk_bf16_f32 v86, v80, v81
	v_mul_f32_e32 v88, 0x3d372713, v83
	v_mul_f32_e32 v88, v83, v88
	v_fma_f32 v88, v83, v88, v83
	v_mul_f32_e32 v88, 0x3f4c422a, v88
	v_add_f32_e32 v88, v88, v88
	v_mul_f32_e32 v88, 0x3fb8aa3b, v88
	v_exp_f32_e32 v88, v88
	v_rcp_f32_e32 v80, v87
	v_add_f32_e32 v81, 1.0, v88
	v_fma_f32 v80, -v82, v80, v82
	v_rcp_f32_e32 v81, v81
	s_nop 0
	v_add_f32_e32 v81, v81, v81
	v_sub_f32_e32 v81, 1.0, v81
	v_mul_f32_e32 v82, 0.5, v83
	v_add_f32_e32 v81, 1.0, v81
	v_mul_f32_e32 v81, v82, v81
	v_mul_f32_e32 v82, v76, v76
	v_fmaak_f32 v82, v247, v82, 0x40135761
	v_mul_f32_e32 v82, v82, v76
	v_exp_f32_e32 v82, v82
	v_cvt_pk_bf16_f32 v87, v80, v81
	v_add_u32_e32 v80, v96, v147
	v_ashrrev_i32_e32 v81, 31, v80
	v_add_f32_e32 v82, 1.0, v82
	v_lshlrev_b64 v[80:81], 10, v[80:81]
	v_lshl_add_u64 v[80:81], s[60:61], 0, v[80:81]
	v_lshl_add_u64 v[80:81], v[80:81], 0, s[18:19]
	v_lshl_add_u64 v[80:81], v[80:81], 0, v[136:137]
	global_store_dwordx4 v[80:81], v[84:87], off
	v_mul_f32_e32 v83, v77, v77
	v_fmaak_f32 v83, v247, v83, 0x40135761
	v_mul_f32_e32 v83, v83, v77
	v_exp_f32_e32 v83, v83
	v_rcp_f32_e32 v81, v82
	v_add_f32_e32 v82, 1.0, v83
	v_fma_f32 v76, -v76, v81, v76
	v_mul_f32_e32 v83, v78, v78
	v_fmaak_f32 v83, v247, v83, 0x40135761
	v_mul_f32_e32 v83, v83, v78
	v_exp_f32_e32 v83, v83
	v_rcp_f32_e32 v81, v82
	v_add_f32_e32 v82, 1.0, v83
	v_fma_f32 v77, -v77, v81, v77
	v_cvt_pk_bf16_f32 v76, v76, v77
	v_mul_f32_e32 v83, v79, v79
	v_fmaak_f32 v83, v247, v83, 0x40135761
	v_mul_f32_e32 v83, v83, v79
	v_exp_f32_e32 v83, v83
	v_rcp_f32_e32 v77, v82
	v_add_f32_e32 v81, 1.0, v83
	v_fma_f32 v77, -v78, v77, v78
	v_mul_f32_e32 v82, v72, v72
	v_fmaak_f32 v82, v247, v82, 0x40135761
	v_mul_f32_e32 v82, v82, v72
	v_exp_f32_e32 v82, v82
	v_rcp_f32_e32 v78, v81
	v_add_f32_e32 v81, 1.0, v82
	v_fma_f32 v78, -v79, v78, v79
	v_cvt_pk_bf16_f32 v77, v77, v78
	v_mul_f32_e32 v82, v73, v73
	v_fmaak_f32 v82, v247, v82, 0x40135761
	v_mul_f32_e32 v82, v82, v73
	v_exp_f32_e32 v82, v82
	v_rcp_f32_e32 v78, v81
	v_add_f32_e32 v79, 1.0, v82
	v_fma_f32 v72, -v72, v78, v72
	v_mul_f32_e32 v81, v74, v74
	v_fmaak_f32 v81, v247, v81, 0x40135761
	v_mul_f32_e32 v81, v81, v74
	v_exp_f32_e32 v81, v81
	v_rcp_f32_e32 v78, v79
	v_add_f32_e32 v79, 1.0, v81
	v_fma_f32 v73, -v73, v78, v73
	v_cvt_pk_bf16_f32 v78, v72, v73
	v_mul_f32_e32 v81, 0x3d372713, v75
	v_mul_f32_e32 v81, v75, v81
	v_fma_f32 v81, v75, v81, v75
	v_mul_f32_e32 v81, 0x3f4c422a, v81
	v_add_f32_e32 v81, v81, v81
	v_mul_f32_e32 v81, 0x3fb8aa3b, v81
	v_exp_f32_e32 v81, v81
	v_rcp_f32_e32 v72, v79
	v_add_f32_e32 v73, 1.0, v81
	v_fma_f32 v72, -v74, v72, v74
	v_rcp_f32_e32 v73, v73
	s_nop 0
	v_add_f32_e32 v73, v73, v73
	v_sub_f32_e32 v73, 1.0, v73
	v_mul_f32_e32 v74, 0.5, v75
	v_add_f32_e32 v73, 1.0, v73
	v_mul_f32_e32 v73, v74, v73
	v_cvt_pk_bf16_f32 v79, v72, v73
	v_mul_f32_e32 v73, 0x3d372713, v68
	v_mul_f32_e32 v73, v68, v73
	v_fma_f32 v73, v68, v73, v68
	v_mul_f32_e32 v73, 0x3f4c422a, v73
	v_add_f32_e32 v73, v73, v73
	v_mul_f32_e32 v73, 0x3fb8aa3b, v73
	v_exp_f32_e32 v74, v73
	v_or_b32_e32 v80, 0x300, v151
	v_add_u32_e32 v72, v80, v146
	v_ashrrev_i32_e32 v73, 31, v72
	v_add_f32_e32 v74, 1.0, v74
	v_lshlrev_b64 v[72:73], 10, v[72:73]
	v_lshl_add_u64 v[72:73], s[60:61], 0, v[72:73]
	v_lshl_add_u64 v[72:73], v[72:73], 0, s[18:19]
	v_lshl_add_u64 v[72:73], v[72:73], 0, v[136:137]
	global_store_dwordx4 v[72:73], v[76:79], off
	v_mul_f32_e32 v75, v69, v69
	v_fmaak_f32 v75, v247, v75, 0x40135761
	v_mul_f32_e32 v75, v75, v69
	v_exp_f32_e32 v75, v75
	v_rcp_f32_e32 v72, v74
	s_nop 0
	v_add_f32_e32 v72, v72, v72
	v_sub_f32_e32 v72, 1.0, v72
	v_add_f32_e32 v73, 1.0, v75
	v_mul_f32_e32 v68, 0.5, v68
	v_add_f32_e32 v72, 1.0, v72
	v_mul_f32_e32 v68, v68, v72
	v_mul_f32_e32 v74, v70, v70
	v_fmaak_f32 v74, v247, v74, 0x40135761
	v_mul_f32_e32 v74, v74, v70
	v_exp_f32_e32 v74, v74
	v_rcp_f32_e32 v72, v73
	v_add_f32_e32 v73, 1.0, v74
	v_fma_f32 v69, -v69, v72, v69
	v_cvt_pk_bf16_f32 v68, v68, v69
	v_mul_f32_e32 v74, v71, v71
	v_fmaak_f32 v74, v247, v74, 0x40135761
	v_mul_f32_e32 v74, v74, v71
	v_exp_f32_e32 v74, v74
	v_rcp_f32_e32 v69, v73
	v_add_f32_e32 v72, 1.0, v74
	v_fma_f32 v69, -v70, v69, v70
	v_mul_f32_e32 v73, v64, v64
	v_fmaak_f32 v73, v247, v73, 0x40135761
	v_mul_f32_e32 v73, v73, v64
	v_exp_f32_e32 v73, v73
	v_rcp_f32_e32 v70, v72
	v_add_f32_e32 v72, 1.0, v73
	v_fma_f32 v70, -v71, v70, v71
	v_cvt_pk_bf16_f32 v69, v69, v70
	v_mul_f32_e32 v73, v65, v65
	v_fmaak_f32 v73, v247, v73, 0x40135761
	v_mul_f32_e32 v73, v73, v65
	v_exp_f32_e32 v73, v73
	v_rcp_f32_e32 v70, v72
	v_add_f32_e32 v71, 1.0, v73
	v_fma_f32 v64, -v64, v70, v64
	v_mul_f32_e32 v72, v66, v66
	v_fmaak_f32 v72, v247, v72, 0x40135761
	v_mul_f32_e32 v72, v72, v66
	v_exp_f32_e32 v72, v72
	v_rcp_f32_e32 v70, v71
	v_add_f32_e32 v71, 1.0, v72
	v_fma_f32 v65, -v65, v70, v65
	v_cvt_pk_bf16_f32 v70, v64, v65
	v_mul_f32_e32 v72, 0x3d372713, v67
	v_mul_f32_e32 v72, v67, v72
	v_fma_f32 v72, v67, v72, v67
	v_mul_f32_e32 v72, 0x3f4c422a, v72
	v_add_f32_e32 v72, v72, v72
	v_mul_f32_e32 v72, 0x3fb8aa3b, v72
	v_exp_f32_e32 v72, v72
	v_rcp_f32_e32 v64, v71
	v_add_f32_e32 v65, 1.0, v72
	v_fma_f32 v64, -v66, v64, v66
	v_rcp_f32_e32 v65, v65
	s_nop 0
	v_add_f32_e32 v65, v65, v65
	v_sub_f32_e32 v65, 1.0, v65
	v_mul_f32_e32 v66, 0.5, v67
	v_add_f32_e32 v65, 1.0, v65
	v_mul_f32_e32 v65, v66, v65
	v_mul_f32_e32 v66, v60, v60
	v_fmaak_f32 v66, v247, v66, 0x40135761
	v_mul_f32_e32 v66, v66, v60
	v_exp_f32_e32 v66, v66
	v_cvt_pk_bf16_f32 v71, v64, v65
	v_add_u32_e32 v64, v80, v147
	v_ashrrev_i32_e32 v65, 31, v64
	v_add_f32_e32 v66, 1.0, v66
	v_lshlrev_b64 v[64:65], 10, v[64:65]
	v_lshl_add_u64 v[64:65], s[60:61], 0, v[64:65]
	v_lshl_add_u64 v[64:65], v[64:65], 0, s[18:19]
	v_lshl_add_u64 v[64:65], v[64:65], 0, v[136:137]
	global_store_dwordx4 v[64:65], v[68:71], off
	v_mul_f32_e32 v67, v61, v61
	v_fmaak_f32 v67, v247, v67, 0x40135761
	v_mul_f32_e32 v67, v67, v61
	v_exp_f32_e32 v67, v67
	v_rcp_f32_e32 v65, v66
	v_add_f32_e32 v66, 1.0, v67
	v_fma_f32 v60, -v60, v65, v60
	v_mul_f32_e32 v67, v62, v62
	v_fmaak_f32 v67, v247, v67, 0x40135761
	v_mul_f32_e32 v67, v67, v62
	v_exp_f32_e32 v67, v67
	v_rcp_f32_e32 v65, v66
	v_add_f32_e32 v66, 1.0, v67
	v_fma_f32 v61, -v61, v65, v61
	v_cvt_pk_bf16_f32 v60, v60, v61
	v_mul_f32_e32 v67, v63, v63
	v_fmaak_f32 v67, v247, v67, 0x40135761
	v_mul_f32_e32 v67, v67, v63
	v_exp_f32_e32 v67, v67
	v_rcp_f32_e32 v61, v66
	v_add_f32_e32 v65, 1.0, v67
	v_fma_f32 v61, -v62, v61, v62
	v_mul_f32_e32 v66, v56, v56
	v_fmaak_f32 v66, v247, v66, 0x40135761
	v_mul_f32_e32 v66, v66, v56
	v_exp_f32_e32 v66, v66
	v_rcp_f32_e32 v62, v65
	v_add_f32_e32 v65, 1.0, v66
	v_fma_f32 v62, -v63, v62, v63
	v_cvt_pk_bf16_f32 v61, v61, v62
	v_mul_f32_e32 v66, v57, v57
	v_fmaak_f32 v66, v247, v66, 0x40135761
	v_mul_f32_e32 v66, v66, v57
	v_exp_f32_e32 v66, v66
	v_rcp_f32_e32 v62, v65
	v_add_f32_e32 v63, 1.0, v66
	v_fma_f32 v56, -v56, v62, v56
	v_mul_f32_e32 v65, v58, v58
	v_fmaak_f32 v65, v247, v65, 0x40135761
	v_mul_f32_e32 v65, v65, v58
	v_exp_f32_e32 v65, v65
	v_rcp_f32_e32 v62, v63
	v_add_f32_e32 v63, 1.0, v65
	v_fma_f32 v57, -v57, v62, v57
	v_cvt_pk_bf16_f32 v62, v56, v57
	v_mul_f32_e32 v65, 0x3d372713, v59
	v_mul_f32_e32 v65, v59, v65
	v_fma_f32 v65, v59, v65, v59
	v_mul_f32_e32 v65, 0x3f4c422a, v65
	v_add_f32_e32 v65, v65, v65
	v_mul_f32_e32 v65, 0x3fb8aa3b, v65
	v_exp_f32_e32 v65, v65
	v_rcp_f32_e32 v56, v63
	v_add_f32_e32 v57, 1.0, v65
	v_fma_f32 v56, -v58, v56, v58
	v_rcp_f32_e32 v57, v57
	s_nop 0
	v_add_f32_e32 v57, v57, v57
	v_sub_f32_e32 v57, 1.0, v57
	v_mul_f32_e32 v58, 0.5, v59
	v_add_f32_e32 v57, 1.0, v57
	v_mul_f32_e32 v57, v58, v57
	v_cvt_pk_bf16_f32 v63, v56, v57
	v_mul_f32_e32 v57, 0x3d372713, v52
	v_mul_f32_e32 v57, v52, v57
	v_fma_f32 v57, v52, v57, v52
	v_mul_f32_e32 v57, 0x3f4c422a, v57
	v_add_f32_e32 v57, v57, v57
	v_mul_f32_e32 v57, 0x3fb8aa3b, v57
	v_exp_f32_e32 v58, v57
	v_add_u32_e32 v64, 0x800, v151
	v_add_u32_e32 v56, v64, v146
	v_ashrrev_i32_e32 v57, 31, v56
	v_add_f32_e32 v58, 1.0, v58
	v_lshlrev_b64 v[56:57], 10, v[56:57]
	v_lshl_add_u64 v[56:57], s[60:61], 0, v[56:57]
	v_lshl_add_u64 v[56:57], v[56:57], 0, s[18:19]
	v_lshl_add_u64 v[56:57], v[56:57], 0, v[136:137]
	global_store_dwordx4 v[56:57], v[60:63], off
	v_mul_f32_e32 v59, v53, v53
	v_fmaak_f32 v59, v247, v59, 0x40135761
	v_mul_f32_e32 v59, v59, v53
	v_exp_f32_e32 v59, v59
	v_rcp_f32_e32 v56, v58
	s_nop 0
	v_add_f32_e32 v56, v56, v56
	v_sub_f32_e32 v56, 1.0, v56
	v_add_f32_e32 v57, 1.0, v59
	v_mul_f32_e32 v52, 0.5, v52
	v_add_f32_e32 v56, 1.0, v56
	v_mul_f32_e32 v52, v52, v56
	v_mul_f32_e32 v58, v54, v54
	v_fmaak_f32 v58, v247, v58, 0x40135761
	v_mul_f32_e32 v58, v58, v54
	v_exp_f32_e32 v58, v58
	v_rcp_f32_e32 v56, v57
	v_add_f32_e32 v57, 1.0, v58
	v_fma_f32 v53, -v53, v56, v53
	v_cvt_pk_bf16_f32 v52, v52, v53
	v_mul_f32_e32 v58, v55, v55
	v_fmaak_f32 v58, v247, v58, 0x40135761
	v_mul_f32_e32 v58, v58, v55
	v_exp_f32_e32 v58, v58
	v_rcp_f32_e32 v53, v57
	v_add_f32_e32 v56, 1.0, v58
	v_fma_f32 v53, -v54, v53, v54
	v_mul_f32_e32 v57, v48, v48
	v_fmaak_f32 v57, v247, v57, 0x40135761
	v_mul_f32_e32 v57, v57, v48
	v_exp_f32_e32 v57, v57
	v_rcp_f32_e32 v54, v56
	v_add_f32_e32 v56, 1.0, v57
	v_fma_f32 v54, -v55, v54, v55
	v_cvt_pk_bf16_f32 v53, v53, v54
	v_mul_f32_e32 v57, v49, v49
	v_fmaak_f32 v57, v247, v57, 0x40135761
	v_mul_f32_e32 v57, v57, v49
	v_exp_f32_e32 v57, v57
	v_rcp_f32_e32 v54, v56
	v_add_f32_e32 v55, 1.0, v57
	v_fma_f32 v48, -v48, v54, v48
	v_mul_f32_e32 v56, v50, v50
	v_fmaak_f32 v56, v247, v56, 0x40135761
	v_mul_f32_e32 v56, v56, v50
	v_exp_f32_e32 v56, v56
	v_rcp_f32_e32 v54, v55
	v_add_f32_e32 v55, 1.0, v56
	v_fma_f32 v49, -v49, v54, v49
	v_cvt_pk_bf16_f32 v54, v48, v49
	v_mul_f32_e32 v56, 0x3d372713, v51
	v_mul_f32_e32 v56, v51, v56
	v_fma_f32 v56, v51, v56, v51
	v_mul_f32_e32 v56, 0x3f4c422a, v56
	v_add_f32_e32 v56, v56, v56
	v_mul_f32_e32 v56, 0x3fb8aa3b, v56
	v_exp_f32_e32 v56, v56
	v_rcp_f32_e32 v48, v55
	v_add_f32_e32 v49, 1.0, v56
	v_fma_f32 v48, -v50, v48, v50
	v_rcp_f32_e32 v49, v49
	s_nop 0
	v_add_f32_e32 v49, v49, v49
	v_sub_f32_e32 v49, 1.0, v49
	v_mul_f32_e32 v50, 0.5, v51
	v_add_f32_e32 v49, 1.0, v49
	v_mul_f32_e32 v49, v50, v49
	v_mul_f32_e32 v50, v44, v44
	v_fmaak_f32 v50, v247, v50, 0x40135761
	v_mul_f32_e32 v50, v50, v44
	v_exp_f32_e32 v50, v50
	v_cvt_pk_bf16_f32 v55, v48, v49
	v_add_u32_e32 v48, v64, v147
	v_ashrrev_i32_e32 v49, 31, v48
	v_add_f32_e32 v50, 1.0, v50
	v_lshlrev_b64 v[48:49], 10, v[48:49]
	v_lshl_add_u64 v[48:49], s[60:61], 0, v[48:49]
	v_lshl_add_u64 v[48:49], v[48:49], 0, s[18:19]
	v_lshl_add_u64 v[48:49], v[48:49], 0, v[136:137]
	global_store_dwordx4 v[48:49], v[52:55], off
	v_mul_f32_e32 v51, v45, v45
	v_fmaak_f32 v51, v247, v51, 0x40135761
	v_mul_f32_e32 v51, v51, v45
	v_exp_f32_e32 v51, v51
	v_rcp_f32_e32 v49, v50
	v_add_f32_e32 v50, 1.0, v51
	v_fma_f32 v44, -v44, v49, v44
	v_mul_f32_e32 v51, v46, v46
	v_fmaak_f32 v51, v247, v51, 0x40135761
	v_mul_f32_e32 v51, v51, v46
	v_exp_f32_e32 v51, v51
	v_rcp_f32_e32 v49, v50
	v_add_f32_e32 v50, 1.0, v51
	v_fma_f32 v45, -v45, v49, v45
	v_cvt_pk_bf16_f32 v44, v44, v45
	v_mul_f32_e32 v51, v47, v47
	v_fmaak_f32 v51, v247, v51, 0x40135761
	v_mul_f32_e32 v51, v51, v47
	v_exp_f32_e32 v51, v51
	v_rcp_f32_e32 v45, v50
	v_add_f32_e32 v49, 1.0, v51
	v_fma_f32 v45, -v46, v45, v46
	v_mul_f32_e32 v50, v40, v40
	v_fmaak_f32 v50, v247, v50, 0x40135761
	v_mul_f32_e32 v50, v50, v40
	v_exp_f32_e32 v50, v50
	v_rcp_f32_e32 v46, v49
	v_add_f32_e32 v49, 1.0, v50
	v_fma_f32 v46, -v47, v46, v47
	v_cvt_pk_bf16_f32 v45, v45, v46
	v_mul_f32_e32 v50, v41, v41
	v_fmaak_f32 v50, v247, v50, 0x40135761
	v_mul_f32_e32 v50, v50, v41
	v_exp_f32_e32 v50, v50
	v_rcp_f32_e32 v46, v49
	v_add_f32_e32 v47, 1.0, v50
	v_fma_f32 v40, -v40, v46, v40
	v_mul_f32_e32 v49, v42, v42
	v_fmaak_f32 v49, v247, v49, 0x40135761
	v_mul_f32_e32 v49, v49, v42
	v_exp_f32_e32 v49, v49
	v_rcp_f32_e32 v46, v47
	v_add_f32_e32 v47, 1.0, v49
	v_fma_f32 v41, -v41, v46, v41
	v_cvt_pk_bf16_f32 v46, v40, v41
	v_mul_f32_e32 v49, 0x3d372713, v43
	v_mul_f32_e32 v49, v43, v49
	v_fma_f32 v49, v43, v49, v43
	v_mul_f32_e32 v49, 0x3f4c422a, v49
	v_add_f32_e32 v49, v49, v49
	v_mul_f32_e32 v49, 0x3fb8aa3b, v49
	v_exp_f32_e32 v49, v49
	v_rcp_f32_e32 v40, v47
	v_add_f32_e32 v41, 1.0, v49
	v_fma_f32 v40, -v42, v40, v42
	v_rcp_f32_e32 v41, v41
	s_nop 0
	v_add_f32_e32 v41, v41, v41
	v_sub_f32_e32 v41, 1.0, v41
	v_mul_f32_e32 v42, 0.5, v43
	v_add_f32_e32 v41, 1.0, v41
	v_mul_f32_e32 v41, v42, v41
	v_cvt_pk_bf16_f32 v47, v40, v41
	v_mul_f32_e32 v41, 0x3d372713, v36
	v_mul_f32_e32 v41, v36, v41
	v_fma_f32 v41, v36, v41, v36
	v_mul_f32_e32 v41, 0x3f4c422a, v41
	v_add_f32_e32 v41, v41, v41
	v_mul_f32_e32 v41, 0x3fb8aa3b, v41
	v_exp_f32_e32 v42, v41
	v_or_b32_e32 v48, 0x100, v64
	v_add_u32_e32 v40, v48, v146
	v_ashrrev_i32_e32 v41, 31, v40
	v_add_f32_e32 v42, 1.0, v42
	v_lshlrev_b64 v[40:41], 10, v[40:41]
	v_lshl_add_u64 v[40:41], s[60:61], 0, v[40:41]
	v_lshl_add_u64 v[40:41], v[40:41], 0, s[18:19]
	v_lshl_add_u64 v[40:41], v[40:41], 0, v[136:137]
	global_store_dwordx4 v[40:41], v[44:47], off
	v_mul_f32_e32 v43, v37, v37
	v_fmaak_f32 v43, v247, v43, 0x40135761
	v_mul_f32_e32 v43, v43, v37
	v_exp_f32_e32 v43, v43
	v_rcp_f32_e32 v40, v42
	s_nop 0
	v_add_f32_e32 v40, v40, v40
	v_sub_f32_e32 v40, 1.0, v40
	v_add_f32_e32 v41, 1.0, v43
	v_mul_f32_e32 v36, 0.5, v36
	v_add_f32_e32 v40, 1.0, v40
	v_mul_f32_e32 v36, v36, v40
	v_mul_f32_e32 v42, v38, v38
	v_fmaak_f32 v42, v247, v42, 0x40135761
	v_mul_f32_e32 v42, v42, v38
	v_exp_f32_e32 v42, v42
	v_rcp_f32_e32 v40, v41
	v_add_f32_e32 v41, 1.0, v42
	v_fma_f32 v37, -v37, v40, v37
	v_cvt_pk_bf16_f32 v36, v36, v37
	v_mul_f32_e32 v42, v39, v39
	v_fmaak_f32 v42, v247, v42, 0x40135761
	v_mul_f32_e32 v42, v42, v39
	v_exp_f32_e32 v42, v42
	v_rcp_f32_e32 v37, v41
	v_add_f32_e32 v40, 1.0, v42
	v_fma_f32 v37, -v38, v37, v38
	v_mul_f32_e32 v41, v32, v32
	v_fmaak_f32 v41, v247, v41, 0x40135761
	v_mul_f32_e32 v41, v41, v32
	v_exp_f32_e32 v41, v41
	v_rcp_f32_e32 v38, v40
	v_add_f32_e32 v40, 1.0, v41
	v_fma_f32 v38, -v39, v38, v39
	v_cvt_pk_bf16_f32 v37, v37, v38
	v_mul_f32_e32 v41, v33, v33
	v_fmaak_f32 v41, v247, v41, 0x40135761
	v_mul_f32_e32 v41, v41, v33
	v_exp_f32_e32 v41, v41
	v_rcp_f32_e32 v38, v40
	v_add_f32_e32 v39, 1.0, v41
	v_fma_f32 v32, -v32, v38, v32
	v_mul_f32_e32 v40, v34, v34
	v_fmaak_f32 v40, v247, v40, 0x40135761
	v_mul_f32_e32 v40, v40, v34
	v_exp_f32_e32 v40, v40
	v_rcp_f32_e32 v38, v39
	v_add_f32_e32 v39, 1.0, v40
	v_fma_f32 v33, -v33, v38, v33
	v_cvt_pk_bf16_f32 v38, v32, v33
	v_mul_f32_e32 v40, 0x3d372713, v35
	v_mul_f32_e32 v40, v35, v40
	v_fma_f32 v40, v35, v40, v35
	v_mul_f32_e32 v40, 0x3f4c422a, v40
	v_add_f32_e32 v40, v40, v40
	v_mul_f32_e32 v40, 0x3fb8aa3b, v40
	v_exp_f32_e32 v40, v40
	v_rcp_f32_e32 v32, v39
	v_add_f32_e32 v33, 1.0, v40
	v_fma_f32 v32, -v34, v32, v34
	v_rcp_f32_e32 v33, v33
	s_nop 0
	v_add_f32_e32 v33, v33, v33
	v_sub_f32_e32 v33, 1.0, v33
	v_mul_f32_e32 v34, 0.5, v35
	v_add_f32_e32 v33, 1.0, v33
	v_mul_f32_e32 v33, v34, v33
	v_mul_f32_e32 v34, v28, v28
	v_fmaak_f32 v34, v247, v34, 0x40135761
	v_mul_f32_e32 v34, v34, v28
	v_exp_f32_e32 v34, v34
	v_cvt_pk_bf16_f32 v39, v32, v33
	v_add_u32_e32 v32, v48, v147
	v_ashrrev_i32_e32 v33, 31, v32
	v_add_f32_e32 v34, 1.0, v34
	v_lshlrev_b64 v[32:33], 10, v[32:33]
	v_lshl_add_u64 v[32:33], s[60:61], 0, v[32:33]
	v_lshl_add_u64 v[32:33], v[32:33], 0, s[18:19]
	v_lshl_add_u64 v[32:33], v[32:33], 0, v[136:137]
	global_store_dwordx4 v[32:33], v[36:39], off
	v_mul_f32_e32 v35, v29, v29
	v_fmaak_f32 v35, v247, v35, 0x40135761
	v_mul_f32_e32 v35, v35, v29
	v_exp_f32_e32 v35, v35
	v_rcp_f32_e32 v33, v34
	v_add_f32_e32 v34, 1.0, v35
	v_fma_f32 v28, -v28, v33, v28
	v_mul_f32_e32 v35, v30, v30
	v_fmaak_f32 v35, v247, v35, 0x40135761
	v_mul_f32_e32 v35, v35, v30
	v_exp_f32_e32 v35, v35
	v_rcp_f32_e32 v33, v34
	v_add_f32_e32 v34, 1.0, v35
	v_fma_f32 v29, -v29, v33, v29
	v_cvt_pk_bf16_f32 v28, v28, v29
	v_mul_f32_e32 v35, v31, v31
	v_fmaak_f32 v35, v247, v35, 0x40135761
	v_mul_f32_e32 v35, v35, v31
	v_exp_f32_e32 v35, v35
	v_rcp_f32_e32 v29, v34
	v_add_f32_e32 v33, 1.0, v35
	v_fma_f32 v29, -v30, v29, v30
	v_mul_f32_e32 v34, v24, v24
	v_fmaak_f32 v34, v247, v34, 0x40135761
	v_mul_f32_e32 v34, v34, v24
	v_exp_f32_e32 v34, v34
	v_rcp_f32_e32 v30, v33
	v_add_f32_e32 v33, 1.0, v34
	v_fma_f32 v30, -v31, v30, v31
	v_cvt_pk_bf16_f32 v29, v29, v30
	v_mul_f32_e32 v34, v25, v25
	v_fmaak_f32 v34, v247, v34, 0x40135761
	v_mul_f32_e32 v34, v34, v25
	v_exp_f32_e32 v34, v34
	v_rcp_f32_e32 v30, v33
	v_add_f32_e32 v31, 1.0, v34
	v_fma_f32 v24, -v24, v30, v24
	v_mul_f32_e32 v33, v26, v26
	v_fmaak_f32 v33, v247, v33, 0x40135761
	v_mul_f32_e32 v33, v33, v26
	v_exp_f32_e32 v33, v33
	v_rcp_f32_e32 v30, v31
	v_add_f32_e32 v31, 1.0, v33
	v_fma_f32 v25, -v25, v30, v25
	v_cvt_pk_bf16_f32 v30, v24, v25
	v_mul_f32_e32 v33, 0x3d372713, v27
	v_mul_f32_e32 v33, v27, v33
	v_fma_f32 v33, v27, v33, v27
	v_mul_f32_e32 v33, 0x3f4c422a, v33
	v_add_f32_e32 v33, v33, v33
	v_mul_f32_e32 v33, 0x3fb8aa3b, v33
	v_exp_f32_e32 v33, v33
	v_rcp_f32_e32 v24, v31
	v_add_f32_e32 v25, 1.0, v33
	v_fma_f32 v24, -v26, v24, v26
	v_rcp_f32_e32 v25, v25
	s_nop 0
	v_add_f32_e32 v25, v25, v25
	v_sub_f32_e32 v25, 1.0, v25
	v_mul_f32_e32 v26, 0.5, v27
	v_add_f32_e32 v25, 1.0, v25
	v_mul_f32_e32 v25, v26, v25
	v_cvt_pk_bf16_f32 v31, v24, v25
	v_mul_f32_e32 v25, 0x3d372713, v20
	v_mul_f32_e32 v25, v20, v25
	v_fma_f32 v25, v20, v25, v20
	v_mul_f32_e32 v25, 0x3f4c422a, v25
	v_add_f32_e32 v25, v25, v25
	v_mul_f32_e32 v25, 0x3fb8aa3b, v25
	v_exp_f32_e32 v26, v25
	v_or_b32_e32 v32, 0x200, v64
	v_add_u32_e32 v24, v32, v146
	v_ashrrev_i32_e32 v25, 31, v24
	v_add_f32_e32 v26, 1.0, v26
	v_lshlrev_b64 v[24:25], 10, v[24:25]
	v_lshl_add_u64 v[24:25], s[60:61], 0, v[24:25]
	v_lshl_add_u64 v[24:25], v[24:25], 0, s[18:19]
	v_lshl_add_u64 v[24:25], v[24:25], 0, v[136:137]
	global_store_dwordx4 v[24:25], v[28:31], off
	v_mul_f32_e32 v27, v21, v21
	v_fmaak_f32 v27, v247, v27, 0x40135761
	v_mul_f32_e32 v27, v27, v21
	v_exp_f32_e32 v27, v27
	v_rcp_f32_e32 v24, v26
	s_nop 0
	v_add_f32_e32 v24, v24, v24
	v_sub_f32_e32 v24, 1.0, v24
	v_add_f32_e32 v25, 1.0, v27
	v_mul_f32_e32 v20, 0.5, v20
	v_add_f32_e32 v24, 1.0, v24
	v_mul_f32_e32 v20, v20, v24
	v_mul_f32_e32 v26, v22, v22
	v_fmaak_f32 v26, v247, v26, 0x40135761
	v_mul_f32_e32 v26, v26, v22
	v_exp_f32_e32 v26, v26
	v_rcp_f32_e32 v24, v25
	v_add_f32_e32 v25, 1.0, v26
	v_fma_f32 v21, -v21, v24, v21
	v_cvt_pk_bf16_f32 v20, v20, v21
	v_mul_f32_e32 v26, v23, v23
	v_fmaak_f32 v26, v247, v26, 0x40135761
	v_mul_f32_e32 v26, v26, v23
	v_exp_f32_e32 v26, v26
	v_rcp_f32_e32 v21, v25
	v_add_f32_e32 v24, 1.0, v26
	v_fma_f32 v21, -v22, v21, v22
	v_mul_f32_e32 v25, v16, v16
	v_fmaak_f32 v25, v247, v25, 0x40135761
	v_mul_f32_e32 v25, v25, v16
	v_exp_f32_e32 v25, v25
	v_rcp_f32_e32 v22, v24
	v_add_f32_e32 v24, 1.0, v25
	v_fma_f32 v22, -v23, v22, v23
	v_cvt_pk_bf16_f32 v21, v21, v22
	v_mul_f32_e32 v25, v17, v17
	v_fmaak_f32 v25, v247, v25, 0x40135761
	v_mul_f32_e32 v25, v25, v17
	v_exp_f32_e32 v25, v25
	v_rcp_f32_e32 v22, v24
	v_add_f32_e32 v23, 1.0, v25
	v_fma_f32 v16, -v16, v22, v16
	v_mul_f32_e32 v24, v18, v18
	v_fmaak_f32 v24, v247, v24, 0x40135761
	v_mul_f32_e32 v24, v24, v18
	v_exp_f32_e32 v24, v24
	v_rcp_f32_e32 v22, v23
	v_add_f32_e32 v23, 1.0, v24
	v_fma_f32 v17, -v17, v22, v17
	v_cvt_pk_bf16_f32 v22, v16, v17
	v_mul_f32_e32 v24, 0x3d372713, v19
	v_mul_f32_e32 v24, v19, v24
	v_fma_f32 v24, v19, v24, v19
	v_mul_f32_e32 v24, 0x3f4c422a, v24
	v_add_f32_e32 v24, v24, v24
	v_mul_f32_e32 v24, 0x3fb8aa3b, v24
	v_exp_f32_e32 v24, v24
	v_rcp_f32_e32 v16, v23
	v_add_f32_e32 v17, 1.0, v24
	v_fma_f32 v16, -v18, v16, v18
	v_rcp_f32_e32 v17, v17
	s_nop 0
	v_add_f32_e32 v17, v17, v17
	v_sub_f32_e32 v17, 1.0, v17
	v_mul_f32_e32 v18, 0.5, v19
	v_add_f32_e32 v17, 1.0, v17
	v_mul_f32_e32 v17, v18, v17
	v_mul_f32_e32 v18, v12, v12
	v_fmaak_f32 v18, v247, v18, 0x40135761
	v_mul_f32_e32 v18, v18, v12
	v_exp_f32_e32 v18, v18
	v_cvt_pk_bf16_f32 v23, v16, v17
	v_add_u32_e32 v16, v32, v147
	v_ashrrev_i32_e32 v17, 31, v16
	v_add_f32_e32 v18, 1.0, v18
	v_lshlrev_b64 v[16:17], 10, v[16:17]
	v_lshl_add_u64 v[16:17], s[60:61], 0, v[16:17]
	v_lshl_add_u64 v[16:17], v[16:17], 0, s[18:19]
	v_lshl_add_u64 v[16:17], v[16:17], 0, v[136:137]
	global_store_dwordx4 v[16:17], v[20:23], off
	v_mul_f32_e32 v19, v13, v13
	v_fmaak_f32 v19, v247, v19, 0x40135761
	v_mul_f32_e32 v19, v19, v13
	v_exp_f32_e32 v19, v19
	v_rcp_f32_e32 v17, v18
	v_add_f32_e32 v18, 1.0, v19
	v_fma_f32 v12, -v12, v17, v12
	v_mul_f32_e32 v19, v14, v14
	v_fmaak_f32 v19, v247, v19, 0x40135761
	v_mul_f32_e32 v19, v19, v14
	v_exp_f32_e32 v19, v19
	v_rcp_f32_e32 v17, v18
	v_add_f32_e32 v18, 1.0, v19
	v_fma_f32 v13, -v13, v17, v13
	v_cvt_pk_bf16_f32 v12, v12, v13
	v_mul_f32_e32 v19, v15, v15
	v_fmaak_f32 v19, v247, v19, 0x40135761
	v_mul_f32_e32 v19, v19, v15
	v_exp_f32_e32 v19, v19
	v_rcp_f32_e32 v13, v18
	v_add_f32_e32 v17, 1.0, v19
	v_fma_f32 v13, -v14, v13, v14
	v_mul_f32_e32 v18, v8, v8
	v_fmaak_f32 v18, v247, v18, 0x40135761
	v_mul_f32_e32 v18, v18, v8
	v_exp_f32_e32 v18, v18
	v_rcp_f32_e32 v14, v17
	v_add_f32_e32 v17, 1.0, v18
	v_fma_f32 v14, -v15, v14, v15
	v_cvt_pk_bf16_f32 v13, v13, v14
	v_mul_f32_e32 v18, v9, v9
	v_fmaak_f32 v18, v247, v18, 0x40135761
	v_mul_f32_e32 v18, v18, v9
	v_exp_f32_e32 v18, v18
	v_rcp_f32_e32 v14, v17
	v_add_f32_e32 v15, 1.0, v18
	v_fma_f32 v8, -v8, v14, v8
	v_mul_f32_e32 v17, v10, v10
	v_fmaak_f32 v17, v247, v17, 0x40135761
	v_mul_f32_e32 v17, v17, v10
	v_exp_f32_e32 v17, v17
	v_rcp_f32_e32 v14, v15
	v_add_f32_e32 v15, 1.0, v17
	v_fma_f32 v9, -v9, v14, v9
	v_cvt_pk_bf16_f32 v14, v8, v9
	v_mul_f32_e32 v17, 0x3d372713, v11
	v_mul_f32_e32 v17, v11, v17
	v_fma_f32 v17, v11, v17, v11
	v_mul_f32_e32 v17, 0x3f4c422a, v17
	v_add_f32_e32 v17, v17, v17
	v_mul_f32_e32 v17, 0x3fb8aa3b, v17
	v_exp_f32_e32 v17, v17
	v_rcp_f32_e32 v8, v15
	v_add_f32_e32 v9, 1.0, v17
	v_fma_f32 v8, -v10, v8, v10
	v_rcp_f32_e32 v9, v9
	s_nop 0
	v_add_f32_e32 v9, v9, v9
	v_sub_f32_e32 v9, 1.0, v9
	v_mul_f32_e32 v10, 0.5, v11
	v_add_f32_e32 v9, 1.0, v9
	v_mul_f32_e32 v9, v10, v9
	v_cvt_pk_bf16_f32 v15, v8, v9
	v_mul_f32_e32 v9, 0x3d372713, v4
	v_mul_f32_e32 v9, v4, v9
	v_fma_f32 v9, v4, v9, v4
	v_mul_f32_e32 v9, 0x3f4c422a, v9
	v_add_f32_e32 v9, v9, v9
	v_mul_f32_e32 v9, 0x3fb8aa3b, v9
	v_exp_f32_e32 v10, v9
	v_or_b32_e32 v16, 0x300, v64
	v_add_u32_e32 v8, v16, v146
	v_ashrrev_i32_e32 v9, 31, v8
	v_add_f32_e32 v10, 1.0, v10
	v_lshlrev_b64 v[8:9], 10, v[8:9]
	v_lshl_add_u64 v[8:9], s[60:61], 0, v[8:9]
	v_lshl_add_u64 v[8:9], v[8:9], 0, s[18:19]
	v_lshl_add_u64 v[8:9], v[8:9], 0, v[136:137]
	global_store_dwordx4 v[8:9], v[12:15], off
	v_mul_f32_e32 v11, v5, v5
	v_fmaak_f32 v11, v247, v11, 0x40135761
	v_mul_f32_e32 v11, v11, v5
	v_exp_f32_e32 v11, v11
	v_rcp_f32_e32 v8, v10
	s_nop 0
	v_add_f32_e32 v8, v8, v8
	v_sub_f32_e32 v8, 1.0, v8
	v_add_f32_e32 v9, 1.0, v11
	v_mul_f32_e32 v4, 0.5, v4
	v_add_f32_e32 v8, 1.0, v8
	v_mul_f32_e32 v4, v4, v8
	v_mul_f32_e32 v10, v6, v6
	v_fmaak_f32 v10, v247, v10, 0x40135761
	v_mul_f32_e32 v10, v10, v6
	v_exp_f32_e32 v10, v10
	v_rcp_f32_e32 v8, v9
	v_add_f32_e32 v9, 1.0, v10
	v_fma_f32 v5, -v5, v8, v5
	v_cvt_pk_bf16_f32 v4, v4, v5
	v_mul_f32_e32 v10, v7, v7
	v_fmaak_f32 v10, v247, v10, 0x40135761
	v_mul_f32_e32 v10, v10, v7
	v_exp_f32_e32 v10, v10
	v_rcp_f32_e32 v5, v9
	v_add_f32_e32 v8, 1.0, v10
	v_fma_f32 v5, -v6, v5, v6
	v_mul_f32_e32 v9, v0, v0
	v_fmaak_f32 v9, v247, v9, 0x40135761
	v_mul_f32_e32 v9, v9, v0
	v_exp_f32_e32 v9, v9
	v_rcp_f32_e32 v6, v8
	v_add_f32_e32 v8, 1.0, v9
	v_fma_f32 v6, -v7, v6, v7
	v_cvt_pk_bf16_f32 v5, v5, v6
	v_mul_f32_e32 v9, v1, v1
	v_fmaak_f32 v9, v247, v9, 0x40135761
	v_mul_f32_e32 v9, v9, v1
	v_exp_f32_e32 v9, v9
	v_rcp_f32_e32 v6, v8
	v_add_f32_e32 v7, 1.0, v9
	v_fma_f32 v0, -v0, v6, v0
	v_mul_f32_e32 v8, v2, v2
	v_fmaak_f32 v8, v247, v8, 0x40135761
	v_mul_f32_e32 v8, v8, v2
	v_exp_f32_e32 v8, v8
	v_rcp_f32_e32 v6, v7
	v_add_f32_e32 v7, 1.0, v8
	v_fma_f32 v1, -v1, v6, v1
	v_cvt_pk_bf16_f32 v6, v0, v1
	v_mul_f32_e32 v8, 0x3d372713, v3
	v_mul_f32_e32 v8, v3, v8
	v_fma_f32 v8, v3, v8, v3
	v_mul_f32_e32 v8, 0x3f4c422a, v8
	v_add_f32_e32 v8, v8, v8
	v_mul_f32_e32 v8, 0x3fb8aa3b, v8
	v_exp_f32_e32 v8, v8
	v_rcp_f32_e32 v0, v7
	v_add_f32_e32 v1, 1.0, v8
	v_fma_f32 v0, -v2, v0, v2
	v_rcp_f32_e32 v1, v1
	s_nop 0
	v_add_f32_e32 v1, v1, v1
	v_sub_f32_e32 v1, 1.0, v1
	v_mul_f32_e32 v2, 0.5, v3
	v_add_f32_e32 v1, 1.0, v1
	v_mul_f32_e32 v1, v2, v1
	v_cvt_pk_bf16_f32 v7, v0, v1
	v_add_u32_e32 v0, v16, v147
	v_ashrrev_i32_e32 v1, 31, v0
	v_lshlrev_b64 v[0:1], 10, v[0:1]
	v_lshl_add_u64 v[0:1], s[60:61], 0, v[0:1]
	v_lshl_add_u64 v[0:1], v[0:1], 0, s[18:19]
	v_lshl_add_u64 v[0:1], v[0:1], 0, v[136:137]
	s_andn2_b64 vcc, exec, s[6:7]
	s_mov_b64 s[6:7], -1
	global_store_dwordx4 v[0:1], v[4:7], off
	s_cbranch_vccnz .LBB0_915
	s_and_b64 vcc, exec, s[4:5]
	s_cbranch_vccnz .LBB0_914
	s_barrier
	s_branch .LBB0_914

	.amdhsa_kernel _Z14fwd_megakernel4Args
		.amdhsa_group_segment_fixed_size 0
		.amdhsa_private_segment_fixed_size 0
		.amdhsa_kernarg_size 544
		.amdhsa_user_sgpr_count 2
		.amdhsa_user_sgpr_dispatch_ptr 0
		.amdhsa_user_sgpr_queue_ptr 0
		.amdhsa_user_sgpr_kernarg_segment_ptr 1
		.amdhsa_user_sgpr_dispatch_id 0
		.amdhsa_user_sgpr_kernarg_preload_length 0
		.amdhsa_user_sgpr_kernarg_preload_offset 0
		.amdhsa_user_sgpr_private_segment_size 0
		.amdhsa_uses_dynamic_stack 0
		.amdhsa_enable_private_segment 0
		.amdhsa_system_sgpr_workgroup_id_x 1
		.amdhsa_system_sgpr_workgroup_id_y 0
		.amdhsa_system_sgpr_workgroup_id_z 0
		.amdhsa_system_sgpr_workgroup_info 0
		.amdhsa_system_vgpr_workitem_id 2
		.amdhsa_next_free_vgpr 248
		.amdhsa_next_free_sgpr 100
		.amdhsa_accum_offset 248
		.amdhsa_reserve_vcc 1
		.amdhsa_float_round_mode_32 0
		.amdhsa_float_round_mode_16_64 0
		.amdhsa_float_denorm_mode_32 3
		.amdhsa_float_denorm_mode_16_64 3
		.amdhsa_dx10_clamp 1
		.amdhsa_ieee_mode 1
		.amdhsa_fp16_overflow 0
		.amdhsa_tg_split 0
		.amdhsa_exception_fp_ieee_invalid_op 0
		.amdhsa_exception_fp_denorm_src 0
		.amdhsa_exception_fp_ieee_div_zero 0
		.amdhsa_exception_fp_ieee_overflow 0
		.amdhsa_exception_fp_ieee_underflow 0
		.amdhsa_exception_fp_ieee_inexact 0
		.amdhsa_exception_int_div_zero 0
	.end_amdhsa_kernel

amdhsa.kernels:
  - .agpr_count:     0
    .args:
      - .offset:         0
        .size:           288
        .value_kind:     by_value
      - .offset:         288
        .size:           4
        .value_kind:     hidden_block_count_x
      - .offset:         292
        .size:           4
        .value_kind:     hidden_block_count_y
      - .offset:         296
        .size:           4
        .value_kind:     hidden_block_count_z
      - .offset:         300
        .size:           2
        .value_kind:     hidden_group_size_x
      - .offset:         302
        .size:           2
        .value_kind:     hidden_group_size_y
      - .offset:         304
        .size:           2
        .value_kind:     hidden_group_size_z
      - .offset:         306
        .size:           2
        .value_kind:     hidden_remainder_x
      - .offset:         308
        .size:           2
        .value_kind:     hidden_remainder_y
      - .offset:         310
        .size:           2
        .value_kind:     hidden_remainder_z
      - .offset:         328
        .size:           8
        .value_kind:     hidden_global_offset_x
      - .offset:         336
        .size:           8
        .value_kind:     hidden_global_offset_y
      - .offset:         344
        .size:           8
        .value_kind:     hidden_global_offset_z
      - .offset:         352
        .size:           2
        .value_kind:     hidden_grid_dims
      - .offset:         376
        .size:           8
        .value_kind:     hidden_multigrid_sync_arg
      - .offset:         408
        .size:           4
        .value_kind:     hidden_dynamic_lds_size
    .group_segment_fixed_size: 0
    .kernarg_segment_align: 8
    .kernarg_segment_size: 544
    .language:       OpenCL C
    .language_version:
      - 2
      - 0
    .max_flat_workgroup_size: 512
    .name:           _Z14fwd_megakernel4Args
    .private_segment_fixed_size: 0
    .sgpr_count:     106
    .sgpr_spill_count: 27
    .symbol:         _Z14fwd_megakernel4Args.kd
    .uniform_work_group_size: 1
    .uses_dynamic_stack: false
    .vgpr_count:     248
    .vgpr_spill_count: 0
    .wavefront_size: 64
